# v7 + one static s_setprio 1 for waves 4-7 at kernel entry and after the attention phase (strategy: static priority for the younger half)
# baseline (speedup 1.0000x reference)
_ZN2mk10fwd_kernelENS_4ArgsE:
	s_load_dwordx4 s[80:83], s[0:1], 0x98
	s_mov_b32 s28, s2
	s_add_u32 s2, s0, 0xa8
	s_addc_u32 s3, s1, 0
	v_and_b32_e32 v218, 0x3ff, v0
	v_writelane_b32 v254, s2, 0
	v_cmp_gt_u32_e32 vcc, 16, v218
	s_nop 0
	v_writelane_b32 v254, s3, 1
	s_and_saveexec_b64 s[2:3], vcc
	v_lshl_add_u32 v1, v218, 2, 0
	v_add_u32_e32 v1, 0x24000, v1
	v_mov_b32_e32 v2, 0
	ds_write_b32 v1, v2
	s_or_b64 exec, exec, s[2:3]
	s_waitcnt lgkmcnt(0)
	s_barrier
	v_cmp_lt_u32_e32 vcc, 0xff, v218
	s_nop 4
	s_cbranch_vccz .Lprio_a
	s_setprio 1
.Lprio_a:
	s_add_u32 s2, s80, 0x7c0000
	s_getreg_b32 s4, hwreg(HW_REG_XCC_ID, 0, 4)
	s_addc_u32 s3, s81, 0
	s_and_b32 s8, s4, 15
	v_cmp_eq_u32_e64 s[6:7], 0, v218
	s_mov_b64 s[4:5], exec
	s_nop 0
	v_writelane_b32 v254, s6, 2
	s_nop 1
	v_writelane_b32 v254, s7, 3
	s_and_b64 s[6:7], s[4:5], s[6:7]
	s_mov_b64 exec, s[6:7]
	s_cbranch_execz .LBB0_5
	s_mov_b64 s[6:7], exec
	v_mbcnt_lo_u32_b32 v1, s6, 0
	v_mbcnt_hi_u32_b32 v1, s7, v1
	v_cmp_eq_u32_e32 vcc, 0, v1
	s_and_b64 s[10:11], exec, vcc
	s_mov_b64 exec, s[10:11]
	s_cbranch_execz .LBB0_5
	s_lshl_b32 s9, s8, 8
	s_bcnt1_i32_b64 s6, s[6:7]
	v_mov_b32_e32 v1, s9
	v_mov_b32_e32 v2, s6
	global_atomic_add v1, v2, s[2:3] offset:1024

.LBB0_128:
	v_cmp_lt_u32_e32 vcc, 0xff, v218
	s_nop 4
	s_cbranch_vccz .Lprio_b
	s_setprio 1
